# past/own: lane-exchange max/sum reductions without select and with half the copies (commutative combine of the swapped pair)
# speedup vs baseline: 1.0048x; 1.0048x over previous
.LBB0_259:
	ds_read_b128 v[64:67], v116
	ds_read_b128 v[72:75], v116 offset:64
	ds_read_b128 v[76:79], v116 offset:2304
	ds_read_b128 v[100:103], v116 offset:2368
	v_mov_b32_e32 v163, v164
	v_add_u32_e32 v164, s0, v121
	s_waitcnt lgkmcnt(1)
	v_mfma_f32_16x16x32_bf16 v[198:201], v[76:79], v[40:43], 0
	v_mov_b32_e32 v165, v166
	v_add_u32_e32 v166, 0x2000, v164
	v_add_u32_e32 v167, 0x4000, v164
	v_mfma_f32_16x16x32_bf16 v[104:107], v[76:79], v[36:39], 0
	ds_read_b128 v[80:83], v116 offset:4608
	ds_read_b128 v[76:79], v116 offset:4672
	s_addk_i32 s0, 0x80
	s_cmpk_eq_i32 s0, 0x200
	v_mfma_f32_16x16x32_bf16 v[68:71], v[64:67], v[40:43], 0
	v_mfma_f32_16x16x32_bf16 v[64:67], v[64:67], v[36:39], 0
	s_waitcnt lgkmcnt(1)
	v_mfma_f32_16x16x32_bf16 v[92:95], v[80:83], v[40:43], 0
	v_mfma_f32_16x16x32_bf16 v[84:87], v[80:83], v[36:39], 0
	ds_read_b128 v[88:91], v116 offset:6912
	ds_read_b128 v[80:83], v116 offset:6976
	v_add_u32_e32 v116, 0x2400, v116
	s_waitcnt lgkmcnt(1)
	v_mfma_f32_16x16x32_bf16 v[96:99], v[88:91], v[40:43], 0
	v_mfma_f32_16x16x32_bf16 v[88:91], v[88:91], v[36:39], 0
	v_mfma_f32_16x16x32_bf16 v[68:71], v[72:75], v[44:47], v[68:71]
	v_mfma_f32_16x16x32_bf16 v[72:75], v[72:75], v[32:35], v[64:67]
	v_mfma_f32_16x16x32_bf16 v[64:67], v[100:103], v[44:47], v[198:201]
	v_mfma_f32_16x16x32_bf16 v[100:103], v[100:103], v[32:35], v[104:107]
	s_nop 2
	ds_read2_b64 v[104:107], v164 offset1:4
	ds_read2_b64 v[198:201], v164 offset0:8 offset1:12
	v_add_u32_e32 v164, 0x6000, v164
	v_mfma_f32_16x16x32_bf16 v[92:95], v[76:79], v[44:47], v[92:95]
	v_mfma_f32_16x16x32_bf16 v[76:79], v[76:79], v[32:35], v[84:87]
	s_nop 2
	ds_read2_b64 v[84:87], v166 offset0:32 offset1:36
	ds_read2_b64 v[202:205], v166 offset0:40 offset1:44
	ds_read2_b64 v[206:209], v167 offset0:64 offset1:68
	ds_read2_b64 v[210:213], v167 offset0:72 offset1:76
	ds_read2_b64 v[214:217], v164 offset0:96 offset1:100
	ds_read2_b64 v[218:221], v164 offset0:104 offset1:108
	s_waitcnt lgkmcnt(8)
	v_mfma_f32_16x16x32_bf16 v[96:99], v[80:83], v[44:47], v[96:99]
	v_mfma_f32_16x16x32_bf16 v[80:83], v[80:83], v[32:35], v[88:91]
	s_nop 2
	v_max3_f32 v88, v68, s4, v69
	v_max3_f32 v89, v72, s4, v73
	v_max3_f32 v88, v88, v70, v71
	v_max3_f32 v89, v89, v74, v75
	v_max3_f32 v88, v88, v64, v65
	v_max3_f32 v89, v89, v100, v101
	v_max3_f32 v88, v88, v66, v67
	v_max3_f32 v89, v89, v102, v103
	v_max3_f32 v88, v88, v92, v93
	v_max3_f32 v89, v89, v76, v77
	v_max3_f32 v88, v88, v94, v95
	v_max3_f32 v89, v89, v78, v79
	v_max3_f32 v88, v88, v96, v97
	v_max3_f32 v89, v89, v80, v81
	v_max3_f32 v88, v88, v98, v99
	v_max3_f32 v89, v89, v82, v83
	v_mov_b32_e32 v90, v88
	v_mov_b32_e32 v91, v89
	s_nop 0
	v_permlane16_swap_b32_e32 v90, v88
	v_permlane16_swap_b32_e32 v91, v89
	v_max_f32_e32 v88, v88, v90
	v_max_f32_e32 v89, v89, v91
	v_mov_b32_e32 v90, v88
	v_mov_b32_e32 v91, v89
	s_nop 0
	v_permlane32_swap_b32_e32 v90, v88
	v_permlane32_swap_b32_e32 v91, v89
	v_max3_f32 v164, v163, v89, v91
	v_max3_f32 v166, v165, v88, v90
	v_sub_f32_e32 v89, v163, v164
	v_sub_f32_e32 v88, v165, v166
	v_sub_f32_e32 v68, v68, v166
	v_sub_f32_e32 v90, v72, v164
	v_sub_f32_e32 v69, v69, v166
	v_sub_f32_e32 v91, v73, v164
	v_sub_f32_e32 v70, v70, v166
	v_sub_f32_e32 v163, v74, v164
	v_sub_f32_e32 v71, v71, v166
	v_sub_f32_e32 v165, v75, v164
	v_sub_f32_e32 v64, v64, v166
	v_sub_f32_e32 v100, v100, v164
	v_sub_f32_e32 v65, v65, v166
	v_sub_f32_e32 v101, v101, v164
	v_sub_f32_e32 v66, v66, v166
	v_sub_f32_e32 v102, v102, v164
	v_sub_f32_e32 v67, v67, v166
	v_sub_f32_e32 v103, v103, v164
	v_exp_f32_e32 v73, v89
	v_sub_f32_e32 v167, v92, v166
	v_sub_f32_e32 v179, v76, v164
	v_sub_f32_e32 v178, v93, v166
	v_sub_f32_e32 v185, v77, v164
	v_sub_f32_e32 v187, v78, v164
	v_sub_f32_e32 v222, v79, v164
	v_sub_f32_e32 v224, v80, v164
	v_sub_f32_e32 v225, v81, v164
	v_sub_f32_e32 v227, v82, v164
	v_sub_f32_e32 v228, v83, v164
	v_exp_f32_e32 v72, v88
	v_exp_f32_e32 v74, v68
	v_exp_f32_e32 v75, v90
	v_exp_f32_e32 v76, v69
	v_exp_f32_e32 v77, v91
	v_exp_f32_e32 v78, v70
	v_exp_f32_e32 v79, v163
	v_exp_f32_e32 v80, v71
	v_exp_f32_e32 v81, v165
	v_exp_f32_e32 v82, v64
	v_exp_f32_e32 v83, v100
	v_exp_f32_e32 v88, v65
	v_exp_f32_e32 v89, v101
	v_exp_f32_e32 v90, v66
	v_exp_f32_e32 v91, v102
	v_exp_f32_e32 v92, v67
	v_exp_f32_e32 v93, v103
	v_sub_f32_e32 v186, v94, v166
	v_sub_f32_e32 v226, v98, v166
	v_exp_f32_e32 v98, v186
	v_mov_b32_e32 v186, v73
	v_sub_f32_e32 v95, v95, v166
	v_sub_f32_e32 v223, v96, v166
	v_sub_f32_e32 v97, v97, v166
	v_sub_f32_e32 v99, v99, v166
	v_pk_mul_f32 v[62:63], v[62:63], v[72:73] op_sel_hi:[1,0]
	v_pk_mul_f32 v[60:61], v[60:61], v[72:73] op_sel_hi:[1,0]
	v_pk_mul_f32 v[58:59], v[58:59], v[72:73] op_sel_hi:[1,0]
	v_cvt_pk_bf16_f32 v64, v74, v76
	v_cvt_pk_bf16_f32 v65, v78, v80
	v_cvt_pk_bf16_f32 v66, v82, v88
	v_cvt_pk_bf16_f32 v67, v90, v92
	v_pk_mul_f32 v[56:57], v[56:57], v[72:73] op_sel_hi:[1,0]
	v_cvt_pk_bf16_f32 v68, v75, v77
	v_cvt_pk_bf16_f32 v69, v79, v81
	v_cvt_pk_bf16_f32 v70, v83, v89
	v_cvt_pk_bf16_f32 v71, v91, v93
	v_pk_mul_f32 v[30:31], v[30:31], v[186:187] op_sel_hi:[1,0]
	v_pk_mul_f32 v[28:29], v[28:29], v[186:187] op_sel_hi:[1,0]
	v_pk_mul_f32 v[26:27], v[26:27], v[186:187] op_sel_hi:[1,0]
	v_pk_mul_f32 v[24:25], v[24:25], v[186:187] op_sel_hi:[1,0]
	v_exp_f32_e32 v94, v167
	v_exp_f32_e32 v96, v178
	v_exp_f32_e32 v100, v95
	v_exp_f32_e32 v102, v223
	v_exp_f32_e32 v178, v97
	s_waitcnt lgkmcnt(7)
	v_mfma_f32_16x16x32_bf16 v[60:63], v[104:107], v[64:67], v[60:63]
	v_mul_f32_e64 v54, v54, v72
	v_mul_f32_e64 v55, v55, v72
	v_pk_mul_f32 v[52:53], v[52:53], v[72:73] op_sel_hi:[1,0]
	v_pk_mul_f32 v[50:51], v[50:51], v[72:73] op_sel_hi:[1,0]
	s_waitcnt lgkmcnt(5)
	v_mfma_f32_16x16x32_bf16 v[56:59], v[84:87], v[64:67], v[56:59]
	v_mul_f32_e64 v48, v48, v72
	v_mul_f32_e64 v49, v49, v72
	v_exp_f32_e32 v95, v179
	v_exp_f32_e32 v97, v185
	v_mfma_f32_16x16x32_bf16 v[28:31], v[104:107], v[68:71], v[28:31]
	v_exp_f32_e32 v104, v226
	v_exp_f32_e32 v101, v222
	v_exp_f32_e32 v103, v224
	v_mfma_f32_16x16x32_bf16 v[24:27], v[84:87], v[68:71], v[24:27]
	v_exp_f32_e32 v84, v99
	v_exp_f32_e32 v99, v187
	v_exp_f32_e32 v179, v225
	s_waitcnt lgkmcnt(3)
	v_mfma_f32_16x16x32_bf16 v[52:55], v[206:209], v[64:67], v[52:55]
	v_exp_f32_e32 v105, v227
	v_pk_mul_f32 v[22:23], v[22:23], v[186:187] op_sel_hi:[1,0]
	v_pk_mul_f32 v[20:21], v[20:21], v[186:187] op_sel_hi:[1,0]
	s_waitcnt lgkmcnt(1)
	v_mfma_f32_16x16x32_bf16 v[48:51], v[214:217], v[64:67], v[48:51]
	v_cvt_pk_bf16_f32 v64, v94, v96
	v_cvt_pk_bf16_f32 v65, v98, v100
	v_cvt_pk_bf16_f32 v66, v102, v178
	v_cvt_pk_bf16_f32 v67, v104, v84
	v_pk_mul_f32 v[18:19], v[18:19], v[186:187] op_sel_hi:[1,0]
	v_pk_mul_f32 v[16:17], v[16:17], v[186:187] op_sel_hi:[1,0]
	v_mfma_f32_16x16x32_bf16 v[60:63], v[198:201], v[64:67], v[60:63]
	v_exp_f32_e32 v85, v228
	v_mfma_f32_16x16x32_bf16 v[56:59], v[202:205], v[64:67], v[56:59]
	v_mfma_f32_16x16x32_bf16 v[52:55], v[210:213], v[64:67], v[52:55]
	s_waitcnt lgkmcnt(0)
	v_mfma_f32_16x16x32_bf16 v[48:51], v[218:221], v[64:67], v[48:51]
	v_add_f32_e64 v64, v74, 0
	v_add_f32_e64 v65, v75, 0
	v_pk_add_f32 v[64:65], v[76:77], v[64:65]
	v_mfma_f32_16x16x32_bf16 v[20:23], v[206:209], v[68:71], v[20:23]
	v_add_f32_e64 v64, v78, v64
	v_add_f32_e64 v65, v79, v65
	v_pk_add_f32 v[64:65], v[80:81], v[64:65]
	v_mfma_f32_16x16x32_bf16 v[16:19], v[214:217], v[68:71], v[16:19]
	v_add_f32_e64 v64, v82, v64
	v_add_f32_e64 v65, v83, v65
	v_cvt_pk_bf16_f32 v68, v95, v97
	v_pk_add_f32 v[64:65], v[88:89], v[64:65]
	v_cvt_pk_bf16_f32 v69, v99, v101
	v_pk_add_f32 v[64:65], v[90:91], v[64:65]
	v_cvt_pk_bf16_f32 v70, v103, v179
	v_pk_add_f32 v[64:65], v[92:93], v[64:65]
	v_cvt_pk_bf16_f32 v71, v105, v85
	v_pk_add_f32 v[64:65], v[94:95], v[64:65]
	s_nop 0
	v_pk_add_f32 v[64:65], v[96:97], v[64:65]
	v_mfma_f32_16x16x32_bf16 v[28:31], v[198:201], v[68:71], v[28:31]
	v_add_f32_e64 v64, v98, v64
	v_add_f32_e64 v65, v99, v65
	v_pk_add_f32 v[64:65], v[100:101], v[64:65]
	v_mfma_f32_16x16x32_bf16 v[24:27], v[202:205], v[68:71], v[24:27]
	v_add_f32_e64 v64, v102, v64
	v_add_f32_e64 v65, v103, v65
	v_pk_add_f32 v[64:65], v[178:179], v[64:65]
	v_mfma_f32_16x16x32_bf16 v[20:23], v[210:213], v[68:71], v[20:23]
	v_add_f32_e64 v64, v104, v64
	v_add_f32_e64 v65, v105, v65
	v_pk_add_f32 v[64:65], v[84:85], v[64:65]
	v_mfma_f32_16x16x32_bf16 v[16:19], v[218:221], v[68:71], v[16:19]
	v_mov_b32_e32 v66, v64
	v_mov_b32_e32 v67, v65
	s_nop 0
	v_permlane16_swap_b32_e32 v66, v64
	v_permlane16_swap_b32_e32 v67, v65
	v_pk_add_f32 v[64:65], v[64:65], v[66:67]
	s_nop 0
	v_mov_b32_e32 v66, v64
	v_mov_b32_e32 v67, v65
	s_nop 0
	v_permlane32_swap_b32_e32 v66, v64
	v_permlane32_swap_b32_e32 v67, v65
	v_pk_add_f32 v[64:65], v[64:65], v[66:67]
	s_nop 0
	v_pk_fma_f32 v[158:159], v[158:159], v[72:73], v[64:65]
	s_cmpk_lg_i32 s0, 0x80
	s_cbranch_scc1 .Lpast_qskip
	v_mov_b32_e32 v233, 0
	s_waitcnt vmcnt(1)
	v_and_b32_e32 v137, 0xfff, v141
	v_lshlrev_b32_e32 v232, 7, v137
	v_lshl_add_u64 v[4:5], v[156:157], 0, v[232:233]
	global_load_dwordx4 v[0:3], v[4:5], off
	s_nop 0
	global_load_dwordx4 v[4:7], v[4:5], off offset:64
	s_waitcnt vmcnt(2)
	v_and_b32_e32 v139, 0xfff, v149
	v_lshlrev_b32_e32 v232, 7, v139
	v_lshl_add_u64 v[12:13], v[156:157], 0, v[232:233]
	global_load_dwordx4 v[8:11], v[12:13], off
	s_nop 0
	global_load_dwordx4 v[12:15], v[12:13], off offset:64

.Lown_wd2:
	s_waitcnt lgkmcnt(1)
	v_mfma_f32_16x16x32_bf16 v[204:207], v[168:171], v[20:23], 0
	v_mfma_f32_16x16x32_bf16 v[168:171], v[168:171], v[28:31], 0
	s_waitcnt lgkmcnt(0)
	v_mfma_f32_16x16x32_bf16 v[204:207], v[200:203], v[24:27], v[204:207]
	v_mfma_f32_16x16x32_bf16 v[168:171], v[200:203], v[32:35], v[168:171]
	ds_read_b128 v[200:203], v67 offset:4608
	ds_read_b128 v[208:211], v67 offset:4672
	ds_read_b128 v[216:219], v67 offset:6912
	ds_read_b128 v[220:223], v67 offset:6976
	v_mfma_f32_16x16x32_bf16 v[164:167], v[156:159], v[20:23], 0
	v_mfma_f32_16x16x32_bf16 v[156:159], v[156:159], v[28:31], 0
	v_mfma_f32_16x16x32_bf16 v[164:167], v[160:163], v[24:27], v[164:167]
	s_waitcnt lgkmcnt(3)
	v_mfma_f32_16x16x32_bf16 v[212:215], v[200:203], v[20:23], 0
	v_mfma_f32_16x16x32_bf16 v[200:203], v[200:203], v[28:31], 0
	s_nop 4
	v_max3_f32 v73, v164, s5, v165
	v_max3_f32 v73, v73, v166, v167
	v_max3_f32 v73, v73, v204, v205
	s_waitcnt lgkmcnt(1)
	v_mfma_f32_16x16x32_bf16 v[224:227], v[216:219], v[20:23], 0
	v_max3_f32 v73, v73, v206, v207
	v_mfma_f32_16x16x32_bf16 v[158:161], v[160:163], v[32:35], v[156:159]
	v_mfma_f32_16x16x32_bf16 v[212:215], v[208:211], v[24:27], v[212:215]
	s_waitcnt lgkmcnt(0)
	v_mfma_f32_16x16x32_bf16 v[224:227], v[220:223], v[24:27], v[224:227]
	s_nop 4
	v_max3_f32 v75, v158, s5, v159
	v_max3_f32 v73, v73, v212, v213
	v_max3_f32 v73, v73, v214, v215
	v_mfma_f32_16x16x32_bf16 v[200:203], v[208:211], v[32:35], v[200:203]
	v_max3_f32 v75, v75, v160, v161
	v_max3_f32 v73, v73, v224, v225
	v_max3_f32 v75, v75, v168, v169
	v_mfma_f32_16x16x32_bf16 v[208:211], v[216:219], v[28:31], 0
	v_max3_f32 v73, v73, v226, v227
	v_max3_f32 v75, v75, v170, v171
	s_nop 1
	v_max3_f32 v75, v75, v200, v201
	v_mfma_f32_16x16x32_bf16 v[208:211], v[220:223], v[32:35], v[208:211]
	v_mov_b32_e32 v95, v73
	v_max3_f32 v75, v75, v202, v203
	s_nop 0
	v_permlane16_swap_b32_e32 v95, v73
	s_nop 3
	v_max3_f32 v75, v75, v208, v209
	v_max3_f32 v75, v75, v210, v211
	v_max_f32_e32 v73, v73, v95
	v_mov_b32_e32 v95, v75
	s_nop 1
	v_permlane16_swap_b32_e32 v95, v75
	v_max_f32_e32 v75, v75, v95
	v_mov_b32_e32 v95, v73
	v_mov_b32_e32 v99, v75
	s_nop 1
	v_permlane32_swap_b32_e32 v95, v73
	v_permlane32_swap_b32_e32 v99, v75
	v_max3_f32 v75, v69, v75, v99
	v_max3_f32 v73, v71, v73, v95
	v_sub_f32_e32 v69, v69, v75
	v_exp_f32_e32 v157, v69
	v_sub_f32_e32 v69, v164, v73
	v_exp_f32_e32 v172, v69
	v_sub_f32_e32 v69, v158, v75
	v_exp_f32_e32 v173, v69
	v_sub_f32_e32 v69, v165, v73
	v_exp_f32_e32 v178, v69
	v_sub_f32_e32 v69, v159, v75
	v_exp_f32_e32 v179, v69
	v_sub_f32_e32 v69, v166, v73
	v_exp_f32_e32 v216, v69
	v_sub_f32_e32 v69, v160, v75
	v_exp_f32_e32 v217, v69
	v_sub_f32_e32 v69, v167, v73
	v_exp_f32_e32 v218, v69
	v_sub_f32_e32 v69, v161, v75
	v_exp_f32_e32 v219, v69
	v_sub_f32_e32 v69, v204, v73
	v_exp_f32_e32 v220, v69
	v_sub_f32_e32 v69, v168, v75
	v_exp_f32_e32 v221, v69
	v_sub_f32_e32 v69, v205, v73
	v_exp_f32_e32 v204, v69
	v_sub_f32_e32 v69, v169, v75
	v_exp_f32_e32 v205, v69
	v_sub_f32_e32 v69, v206, v73
	v_exp_f32_e32 v222, v69
	v_sub_f32_e32 v69, v170, v75
	v_exp_f32_e32 v223, v69
	v_sub_f32_e32 v69, v207, v73
	v_exp_f32_e32 v206, v69
	v_sub_f32_e32 v69, v171, v75
	v_exp_f32_e32 v207, v69
	v_sub_f32_e32 v69, v212, v73
	v_exp_f32_e32 v228, v69
	v_sub_f32_e32 v69, v200, v75
	v_exp_f32_e32 v229, v69
	v_sub_f32_e32 v69, v213, v73
	v_exp_f32_e32 v212, v69
	v_sub_f32_e32 v69, v201, v75
	v_exp_f32_e32 v213, v69
	v_sub_f32_e32 v69, v214, v73
	v_exp_f32_e32 v230, v69
	v_sub_f32_e32 v69, v202, v75
	v_pk_add_f32 v[158:159], v[172:173], 0 op_sel_hi:[1,0]
	v_exp_f32_e32 v231, v69
	v_sub_f32_e32 v69, v215, v73
	v_pk_add_f32 v[158:159], v[178:179], v[158:159]
	v_exp_f32_e32 v214, v69
	v_sub_f32_e32 v69, v203, v75
	v_pk_add_f32 v[158:159], v[216:217], v[158:159]
	v_exp_f32_e32 v215, v69
	v_sub_f32_e32 v69, v224, v73
	ds_read2_b64 v[166:169], v65 offset1:4
	v_pk_add_f32 v[158:159], v[218:219], v[158:159]
	v_exp_f32_e32 v232, v69
	v_sub_f32_e32 v69, v208, v75
	v_pk_add_f32 v[158:159], v[220:221], v[158:159]
	v_exp_f32_e32 v233, v69
	v_sub_f32_e32 v69, v225, v73
	v_sub_f32_e32 v71, v71, v73
	v_pk_add_f32 v[158:159], v[204:205], v[158:159]
	v_exp_f32_e32 v208, v69
	v_sub_f32_e32 v69, v209, v75
	v_exp_f32_e32 v156, v71
	v_pk_add_f32 v[158:159], v[222:223], v[158:159]
	v_exp_f32_e32 v209, v69
	v_sub_f32_e32 v69, v226, v73
	ds_read2_b64 v[200:203], v65 offset0:8 offset1:12
	v_pk_add_f32 v[170:171], v[206:207], v[158:159]
	v_exp_f32_e32 v224, v69
	v_sub_f32_e32 v69, v210, v75
	v_exp_f32_e32 v225, v69
	v_sub_f32_e32 v69, v227, v73
	v_pk_add_f32 v[170:171], v[228:229], v[170:171]
	v_exp_f32_e32 v210, v69
	v_sub_f32_e32 v69, v211, v75
	v_cvt_pk_bf16_f32 v158, v172, v178
	v_pk_add_f32 v[170:171], v[212:213], v[170:171]
	v_mov_b32_e32 v178, v157
	v_exp_f32_e32 v211, v69
	v_pk_mul_f32 v[46:47], v[46:47], v[156:157] op_sel_hi:[1,0]
	v_pk_mul_f32 v[44:45], v[44:45], v[156:157] op_sel_hi:[1,0]
	v_cvt_pk_bf16_f32 v159, v216, v218
	v_cvt_pk_bf16_f32 v160, v220, v204
	v_cvt_pk_bf16_f32 v161, v222, v206
	v_pk_add_f32 v[226:227], v[230:231], v[170:171]
	v_pk_mul_f32 v[14:15], v[14:15], v[178:179] op_sel_hi:[1,0]
	v_pk_mul_f32 v[12:13], v[12:13], v[178:179] op_sel_hi:[1,0]
	v_cvt_pk_bf16_f32 v170, v173, v179
	v_cvt_pk_bf16_f32 v171, v217, v219
	v_cvt_pk_bf16_f32 v172, v221, v205
	v_cvt_pk_bf16_f32 v173, v223, v207
	s_waitcnt lgkmcnt(1)
	v_mfma_f32_16x16x32_bf16 v[44:47], v[166:169], v[158:161], v[44:47]
	v_add_u32_e32 v69, 0x2000, v65
	ds_read2_b64 v[204:207], v69 offset0:32 offset1:36
	v_cvt_pk_bf16_f32 v162, v228, v212
	v_mfma_f32_16x16x32_bf16 v[12:15], v[166:169], v[170:173], v[12:15]
	v_cvt_pk_bf16_f32 v163, v230, v214
	v_cvt_pk_bf16_f32 v164, v232, v208
	v_cvt_pk_bf16_f32 v165, v224, v210
	v_cvt_pk_bf16_f32 v166, v229, v213
	v_cvt_pk_bf16_f32 v167, v231, v215
	v_cvt_pk_bf16_f32 v168, v233, v209
	v_cvt_pk_bf16_f32 v169, v225, v211
	s_waitcnt lgkmcnt(1)
	v_mfma_f32_16x16x32_bf16 v[44:47], v[200:203], v[162:165], v[44:47]
	v_mul_f32_e64 v42, v42, v156
	v_mul_f32_e64 v43, v43, v156
	v_pk_mul_f32 v[40:41], v[40:41], v[156:157] op_sel_hi:[1,0]
	v_pk_mul_f32 v[10:11], v[10:11], v[178:179] op_sel_hi:[1,0]
	v_mfma_f32_16x16x32_bf16 v[12:15], v[200:203], v[166:169], v[12:15]
	v_add_f32_e64 v200, v214, v226
	v_add_f32_e64 v201, v215, v227
	v_pk_mul_f32 v[8:9], v[8:9], v[178:179] op_sel_hi:[1,0]
	v_pk_add_f32 v[212:213], v[232:233], v[200:201]
	ds_read2_b64 v[200:203], v69 offset0:40 offset1:44
	v_add_u32_e32 v69, 0x4000, v65
	s_waitcnt lgkmcnt(1)
	v_mfma_f32_16x16x32_bf16 v[40:43], v[204:207], v[158:161], v[40:43]
	v_add_f32_e64 v208, v208, v212
	v_add_f32_e64 v209, v209, v213
	v_pk_mul_f32 v[38:39], v[38:39], v[156:157] op_sel_hi:[1,0]
	v_pk_add_f32 v[208:209], v[224:225], v[208:209]
	v_mfma_f32_16x16x32_bf16 v[8:11], v[204:207], v[170:173], v[8:11]
	ds_read2_b64 v[204:207], v69 offset0:64 offset1:68
	v_pk_add_f32 v[208:209], v[210:211], v[208:209]
	v_pk_mul_f32 v[36:37], v[36:37], v[156:157] op_sel_hi:[1,0]
	s_waitcnt lgkmcnt(1)
	v_mfma_f32_16x16x32_bf16 v[40:43], v[200:203], v[162:165], v[40:43]
	v_mov_b32_e32 v99, v209
	v_pk_mul_f32 v[6:7], v[6:7], v[178:179] op_sel_hi:[1,0]
	v_pk_mul_f32 v[4:5], v[4:5], v[178:179] op_sel_hi:[1,0]
	v_mfma_f32_16x16x32_bf16 v[8:11], v[200:203], v[166:169], v[8:11]
	ds_read2_b64 v[200:203], v69 offset0:72 offset1:76
	v_mov_b32_e32 v69, v209
	s_nop 1
	v_permlane16_swap_b32_e32 v99, v69
	v_cndmask_b32_e64 v211, v99, v69, s[8:9]
	v_add_u32_e32 v69, 0x6000, v65
	s_waitcnt lgkmcnt(1)
	v_mfma_f32_16x16x32_bf16 v[36:39], v[204:207], v[158:161], v[36:39]
	v_mul_f32_e64 v18, v18, v156
	v_mul_f32_e64 v19, v19, v156
	v_pk_mul_f32 v[16:17], v[16:17], v[156:157] op_sel_hi:[1,0]
	v_mov_b32_e32 v71, v208
	v_mfma_f32_16x16x32_bf16 v[4:7], v[204:207], v[170:173], v[4:7]
	ds_read2_b64 v[204:207], v69 offset0:96 offset1:100
	v_mov_b32_e32 v95, v208
	v_pk_mul_f32 v[2:3], v[2:3], v[178:179] op_sel_hi:[1,0]
	s_waitcnt lgkmcnt(1)
	v_mfma_f32_16x16x32_bf16 v[36:39], v[200:203], v[162:165], v[36:39]
	v_mul_f32_e64 v0, v0, v178
	v_mul_f32_e64 v1, v1, v178
	v_permlane16_swap_b32_e32 v71, v95
	v_mfma_f32_16x16x32_bf16 v[4:7], v[200:203], v[166:169], v[4:7]
	ds_read2_b64 v[200:203], v69 offset0:104 offset1:108
	v_cndmask_b32_e64 v210, v71, v95, s[8:9]
	v_pk_add_f32 v[208:209], v[208:209], v[210:211]
	s_waitcnt lgkmcnt(1)
	v_mfma_f32_16x16x32_bf16 v[16:19], v[204:207], v[158:161], v[16:19]
	v_mov_b32_e32 v71, v208
	v_mov_b32_e32 v95, v208
	v_mov_b32_e32 v99, v209
	v_mfma_f32_16x16x32_bf16 v[0:3], v[204:207], v[170:173], v[0:3]
	v_mov_b32_e32 v69, v209
	v_permlane32_swap_b32_e32 v71, v95
	s_nop 0
	v_permlane32_swap_b32_e32 v99, v69
	s_waitcnt lgkmcnt(0)
	v_mfma_f32_16x16x32_bf16 v[16:19], v[200:203], v[162:165], v[16:19]
	v_cndmask_b32_e64 v159, v99, v69, s[10:11]
	v_cndmask_b32_e64 v158, v71, v95, s[10:11]
	v_pk_add_f32 v[158:159], v[208:209], v[158:159]
	v_mfma_f32_16x16x32_bf16 v[0:3], v[200:203], v[166:169], v[0:3]
	v_fma_f32 v114, v114, v156, v158
	v_fma_f32 v115, v115, v157, v159
	v_mov_b32_e32 v71, v73
	v_mov_b32_e32 v69, v75

.Lown_wd3:
	s_waitcnt lgkmcnt(5)
	v_mfma_f32_16x16x32_bf16 v[164:167], v[156:159], v[20:23], 0
	v_cmp_le_u32_e32 vcc, v73, v49
	v_cmp_lt_u32_e64 s[0:1], v73, v49
	v_add_u32_e32 v75, 16, v73
	v_mfma_f32_16x16x32_bf16 v[156:159], v[156:159], v[28:31], 0
	v_add_u32_e32 v139, 2, v73
	v_add_u32_e32 v149, 3, v73
	s_waitcnt lgkmcnt(3)
	v_mfma_f32_16x16x32_bf16 v[216:219], v[168:171], v[20:23], 0
	v_mfma_f32_16x16x32_bf16 v[168:171], v[168:171], v[28:31], 0
	v_mfma_f32_16x16x32_bf16 v[156:159], v[160:163], v[32:35], v[156:159]
	v_mfma_f32_16x16x32_bf16 v[164:167], v[160:163], v[24:27], v[164:167]
	ds_read_b128 v[160:163], v67 offset:6912
	ds_read_b128 v[212:215], v67 offset:6976
	s_nop 4
	v_cndmask_b32_e32 v95, v198, v156, vcc
	v_cmp_gt_u32_e32 vcc, v73, v55
	s_waitcnt lgkmcnt(4)
	v_mfma_f32_16x16x32_bf16 v[168:171], v[200:203], v[32:35], v[168:171]
	v_cndmask_b32_e64 v103, v198, v157, s[0:1]
	v_cmp_lt_u32_e64 s[0:1], v73, v48
	v_cndmask_b32_e32 v99, v164, v198, vcc
	v_mfma_f32_16x16x32_bf16 v[216:219], v[200:203], v[24:27], v[216:219]
	v_cndmask_b32_e64 v105, v198, v165, s[0:1]
	v_cmp_le_u32_e64 s[0:1], v139, v49
	s_nop 1
	v_cndmask_b32_e32 v172, v168, v198, vcc
	s_waitcnt lgkmcnt(3)
	v_mfma_f32_16x16x32_bf16 v[200:203], v[204:207], v[20:23], 0
	v_cmp_le_u32_e32 vcc, v75, v54
	v_add_u32_e32 v168, 17, v73
	v_cndmask_b32_e64 v141, v198, v158, s[0:1]
	v_cmp_le_u32_e64 s[0:1], v139, v48
	v_cndmask_b32_e32 v75, v198, v216, vcc
	v_cmp_le_u32_e32 vcc, v168, v49
	v_cndmask_b32_e64 v139, v198, v166, s[0:1]
	v_cmp_le_u32_e64 s[0:1], v149, v49
	v_cndmask_b32_e32 v173, v198, v169, vcc
	v_cmp_le_u32_e32 vcc, v168, v48
	v_add_u32_e32 v168, 18, v73
	v_cndmask_b32_e64 v153, v198, v159, s[0:1]
	v_cmp_le_u32_e64 s[0:1], v149, v48
	v_cndmask_b32_e32 v178, v198, v217, vcc
	v_cmp_le_u32_e32 vcc, v168, v49
	v_cndmask_b32_e64 v149, v198, v167, s[0:1]
	s_waitcnt lgkmcnt(2)
	v_mfma_f32_16x16x32_bf16 v[164:167], v[208:211], v[24:27], v[200:203]
	v_cndmask_b32_e32 v179, v198, v170, vcc
	v_cmp_le_u32_e32 vcc, v168, v48
	v_add_u32_e32 v168, 19, v73
	v_mfma_f32_16x16x32_bf16 v[156:159], v[204:207], v[28:31], 0
	v_cndmask_b32_e32 v199, v198, v218, vcc
	v_cmp_le_u32_e32 vcc, v168, v49
	v_add_u32_e32 v169, 48, v73
	v_mfma_f32_16x16x32_bf16 v[156:159], v[208:211], v[32:35], v[156:159]
	v_cndmask_b32_e32 v204, v198, v171, vcc
	v_cmp_le_u32_e32 vcc, v168, v48
	v_add_u32_e32 v168, 32, v73
	s_waitcnt lgkmcnt(1)
	v_mfma_f32_16x16x32_bf16 v[200:203], v[160:163], v[20:23], 0
	v_cndmask_b32_e32 v205, v198, v219, vcc
	v_cmp_le_u32_e32 vcc, v168, v48
	v_max3_f32 v209, v95, s5, v103
	v_mfma_f32_16x16x32_bf16 v[160:163], v[160:163], v[28:31], 0
	v_cndmask_b32_e32 v206, v198, v164, vcc
	v_add_u32_e32 v164, 33, v73
	v_cmp_le_u32_e32 vcc, v164, v48
	v_max3_f32 v209, v209, v141, v153
	v_max3_f32 v209, v209, v172, v173
	v_cndmask_b32_e32 v207, v198, v165, vcc
	v_add_u32_e32 v165, 34, v73
	v_cmp_le_u32_e32 vcc, v165, v48
	s_waitcnt lgkmcnt(0)
	v_mfma_f32_16x16x32_bf16 v[160:163], v[212:215], v[32:35], v[160:163]
	v_max3_f32 v209, v209, v179, v204
	v_cndmask_b32_e32 v208, v198, v166, vcc
	v_cmp_le_u32_e32 vcc, v168, v49
	v_add_u32_e32 v166, 35, v73
	v_mfma_f32_16x16x32_bf16 v[200:203], v[212:215], v[24:27], v[200:203]
	v_cndmask_b32_e32 v210, v198, v156, vcc
	v_cmp_le_u32_e32 vcc, v164, v49
	v_add_u32_e32 v170, 49, v73
	v_max3_f32 v137, v99, s5, v105
	v_cndmask_b32_e32 v211, v198, v157, vcc
	v_cmp_le_u32_e32 vcc, v165, v49
	v_max3_f32 v156, v209, v210, v211
	v_max3_f32 v137, v137, v139, v149
	v_cndmask_b32_e32 v209, v198, v158, vcc
	v_cmp_le_u32_e32 vcc, v166, v49
	v_add_u32_e32 v171, 50, v73
	v_max3_f32 v137, v137, v75, v178
	v_cndmask_b32_e32 v212, v198, v159, vcc
	v_cmp_le_u32_e32 vcc, v166, v48
	v_max3_f32 v137, v137, v199, v205
	v_add_u32_e32 v73, 51, v73
	v_cndmask_b32_e32 v213, v198, v167, vcc
	v_cmp_le_u32_e32 vcc, v169, v49
	v_max3_f32 v137, v137, v206, v207
	v_max3_f32 v137, v137, v208, v213
	v_cndmask_b32_e32 v214, v198, v160, vcc
	v_cmp_le_u32_e32 vcc, v169, v48
	v_max3_f32 v156, v156, v209, v212
	s_nop 0
	v_cndmask_b32_e32 v200, v198, v200, vcc
	v_cmp_le_u32_e32 vcc, v170, v49
	s_nop 1
	v_cndmask_b32_e32 v215, v198, v161, vcc
	v_cmp_le_u32_e32 vcc, v170, v48
	v_max3_f32 v156, v156, v214, v215
	s_nop 0
	v_cndmask_b32_e32 v201, v198, v201, vcc
	v_cmp_le_u32_e32 vcc, v171, v49
	v_max3_f32 v137, v137, v200, v201
	s_nop 0
	v_cndmask_b32_e32 v228, v198, v162, vcc
	v_cmp_le_u32_e32 vcc, v171, v48
	s_nop 1
	v_cndmask_b32_e32 v202, v198, v202, vcc
	v_cmp_le_u32_e32 vcc, v73, v49
	s_nop 1
	v_cndmask_b32_e32 v230, v198, v163, vcc
	v_cmp_le_u32_e32 vcc, v73, v48
	v_max3_f32 v156, v156, v228, v230
	s_nop 0
	v_cndmask_b32_e32 v73, v198, v203, vcc
	v_max3_f32 v137, v137, v202, v73
	v_mov_b32_e32 v157, v137
	s_nop 1
	v_permlane16_swap_b32_e32 v157, v137
	v_max_f32_e32 v137, v137, v157
	v_mov_b32_e32 v157, v156
	s_nop 1
	v_permlane16_swap_b32_e32 v157, v156
	v_max_f32_e32 v157, v156, v157
	v_mov_b32_e32 v156, v137
	v_mov_b32_e32 v158, v157
	s_nop 1
	v_permlane32_swap_b32_e32 v156, v137
	v_permlane32_swap_b32_e32 v158, v157
	v_max3_f32 v232, v69, v157, v158
	v_sub_f32_e32 v69, v69, v232
	v_exp_f32_e32 v157, v69
	v_sub_f32_e32 v69, v95, v232
	v_exp_f32_e32 v69, v69
	v_max3_f32 v137, v71, v137, v156
	v_sub_f32_e32 v71, v71, v137
	v_exp_f32_e32 v156, v71
	v_sub_f32_e32 v71, v99, v137
	v_cmp_lt_f32_e32 vcc, s22, v95
	v_exp_f32_e32 v71, v71
	v_pk_mul_f32 v[42:43], v[42:43], v[156:157] op_sel_hi:[1,0]
	v_cndmask_b32_e32 v159, 0, v69, vcc
	v_sub_f32_e32 v69, v103, v232
	v_exp_f32_e32 v69, v69
	v_cmp_lt_f32_e32 vcc, s22, v99
	v_pk_mul_f32 v[40:41], v[40:41], v[156:157] op_sel_hi:[1,0]
	v_add_u32_e32 v95, 0x4000, v65
	v_cndmask_b32_e32 v158, 0, v71, vcc
	v_sub_f32_e32 v71, v105, v137
	v_cmp_lt_f32_e32 vcc, s22, v103
	v_exp_f32_e32 v71, v71
	v_pk_add_f32 v[162:163], v[158:159], 0 op_sel_hi:[1,0]
	v_cndmask_b32_e32 v161, 0, v69, vcc
	v_sub_f32_e32 v69, v141, v232
	v_exp_f32_e32 v69, v69
	v_cmp_lt_f32_e32 vcc, s22, v105
	v_pk_mul_f32 v[46:47], v[46:47], v[156:157] op_sel_hi:[1,0]
	v_pk_mul_f32 v[44:45], v[44:45], v[156:157] op_sel_hi:[1,0]
	v_cndmask_b32_e32 v160, 0, v71, vcc
	v_sub_f32_e32 v71, v139, v137
	v_cmp_lt_f32_e32 vcc, s22, v141
	v_pk_add_f32 v[164:165], v[160:161], v[162:163]
	v_exp_f32_e32 v71, v71
	v_cndmask_b32_e32 v163, 0, v69, vcc
	v_sub_f32_e32 v69, v153, v232
	v_exp_f32_e32 v69, v69
	v_cmp_lt_f32_e32 vcc, s22, v139
	v_pk_mul_f32 v[38:39], v[38:39], v[156:157] op_sel_hi:[1,0]
	v_pk_mul_f32 v[36:37], v[36:37], v[156:157] op_sel_hi:[1,0]
	v_cndmask_b32_e32 v162, 0, v71, vcc
	v_sub_f32_e32 v71, v149, v137
	v_cmp_lt_f32_e32 vcc, s22, v153
	v_pk_add_f32 v[166:167], v[162:163], v[164:165]
	v_exp_f32_e32 v71, v71
	v_cndmask_b32_e32 v165, 0, v69, vcc
	v_sub_f32_e32 v69, v172, v232
	v_exp_f32_e32 v69, v69
	v_cmp_lt_f32_e32 vcc, s22, v149
	v_pk_mul_f32 v[18:19], v[18:19], v[156:157] op_sel_hi:[1,0]
	v_pk_mul_f32 v[16:17], v[16:17], v[156:157] op_sel_hi:[1,0]
	v_cndmask_b32_e32 v164, 0, v71, vcc
	v_sub_f32_e32 v71, v75, v137
	v_cmp_lt_f32_e32 vcc, s22, v172
	v_pk_add_f32 v[168:169], v[164:165], v[166:167]
	v_exp_f32_e32 v71, v71
	v_cndmask_b32_e32 v167, 0, v69, vcc
	v_sub_f32_e32 v69, v173, v232
	v_exp_f32_e32 v69, v69
	v_cmp_lt_f32_e32 vcc, s22, v75
	s_nop 1
	v_cndmask_b32_e32 v166, 0, v71, vcc
	v_sub_f32_e32 v71, v178, v137
	v_cmp_lt_f32_e32 vcc, s22, v173
	v_pk_add_f32 v[170:171], v[166:167], v[168:169]
	v_exp_f32_e32 v71, v71
	v_cndmask_b32_e32 v169, 0, v69, vcc
	v_sub_f32_e32 v69, v179, v232
	v_exp_f32_e32 v69, v69
	v_cmp_lt_f32_e32 vcc, s22, v178
	s_nop 1
	v_cndmask_b32_e32 v168, 0, v71, vcc
	v_sub_f32_e32 v71, v199, v137
	v_cmp_lt_f32_e32 vcc, s22, v179
	v_pk_add_f32 v[172:173], v[168:169], v[170:171]
	v_exp_f32_e32 v71, v71
	v_cndmask_b32_e32 v171, 0, v69, vcc
	v_sub_f32_e32 v69, v204, v232
	v_exp_f32_e32 v69, v69
	v_cmp_lt_f32_e32 vcc, s22, v199
	s_nop 1
	v_cndmask_b32_e32 v170, 0, v71, vcc
	v_sub_f32_e32 v71, v205, v137
	v_cmp_lt_f32_e32 vcc, s22, v204
	v_pk_add_f32 v[178:179], v[170:171], v[172:173]
	v_exp_f32_e32 v71, v71
	v_cndmask_b32_e32 v173, 0, v69, vcc
	v_sub_f32_e32 v69, v206, v137
	v_exp_f32_e32 v69, v69
	v_cmp_lt_f32_e32 vcc, s22, v205
	s_nop 1
	v_cndmask_b32_e32 v172, 0, v71, vcc
	v_sub_f32_e32 v71, v210, v232
	v_cmp_lt_f32_e32 vcc, s22, v206
	v_exp_f32_e32 v71, v71
	v_pk_add_f32 v[178:179], v[172:173], v[178:179]
	v_cndmask_b32_e32 v216, 0, v69, vcc
	v_sub_f32_e32 v69, v211, v232
	v_exp_f32_e32 v69, v69
	v_cmp_lt_f32_e32 vcc, s22, v210
	v_cvt_pk_bf16_f32 v203, v170, v172
	s_nop 0
	v_cndmask_b32_e32 v217, 0, v71, vcc
	v_sub_f32_e32 v71, v207, v137
	v_cmp_lt_f32_e32 vcc, s22, v211
	v_exp_f32_e32 v71, v71
	v_pk_add_f32 v[178:179], v[216:217], v[178:179]
	v_cndmask_b32_e32 v219, 0, v69, vcc
	v_sub_f32_e32 v69, v209, v232
	v_exp_f32_e32 v69, v69
	v_cmp_lt_f32_e32 vcc, s22, v207
	s_nop 1
	v_cndmask_b32_e32 v218, 0, v71, vcc
	v_sub_f32_e32 v71, v208, v137
	v_cmp_lt_f32_e32 vcc, s22, v209
	v_exp_f32_e32 v71, v71
	v_cvt_pk_bf16_f32 v204, v216, v218
	v_cndmask_b32_e32 v221, 0, v69, vcc
	v_sub_f32_e32 v69, v212, v232
	v_exp_f32_e32 v69, v69
	v_cmp_lt_f32_e32 vcc, s22, v208
	v_mov_b32_e32 v216, v157
	v_pk_add_f32 v[178:179], v[218:219], v[178:179]
	v_cndmask_b32_e32 v220, 0, v71, vcc
	v_sub_f32_e32 v71, v213, v137
	v_cmp_lt_f32_e32 vcc, s22, v212
	v_exp_f32_e32 v71, v71
	ds_read2_b64 v[208:211], v65 offset1:4
	v_cndmask_b32_e32 v223, 0, v69, vcc
	v_sub_f32_e32 v69, v214, v232
	v_exp_f32_e32 v69, v69
	v_cmp_lt_f32_e32 vcc, s22, v213
	v_pk_mul_f32 v[10:11], v[10:11], v[216:217] op_sel_hi:[1,0]
	v_pk_mul_f32 v[8:9], v[8:9], v[216:217] op_sel_hi:[1,0]
	v_cndmask_b32_e32 v222, 0, v71, vcc
	v_sub_f32_e32 v71, v200, v137
	v_cmp_lt_f32_e32 vcc, s22, v214
	v_exp_f32_e32 v71, v71
	v_pk_add_f32 v[178:179], v[220:221], v[178:179]
	v_cndmask_b32_e32 v225, 0, v69, vcc
	v_sub_f32_e32 v69, v215, v232
	v_exp_f32_e32 v69, v69
	v_cmp_lt_f32_e32 vcc, s22, v200
	v_cvt_pk_bf16_f32 v200, v158, v160
	v_cvt_pk_bf16_f32 v160, v167, v169
	v_cndmask_b32_e32 v224, 0, v71, vcc
	v_sub_f32_e32 v71, v201, v137
	v_cmp_lt_f32_e32 vcc, s22, v215
	v_exp_f32_e32 v71, v71
	v_cvt_pk_bf16_f32 v158, v159, v161
	v_cndmask_b32_e32 v227, 0, v69, vcc
	v_sub_f32_e32 v69, v228, v232
	v_exp_f32_e32 v69, v69
	v_cmp_lt_f32_e32 vcc, s22, v201
	v_cvt_pk_bf16_f32 v161, v171, v173
	v_cvt_pk_bf16_f32 v201, v162, v164
	v_cndmask_b32_e32 v226, 0, v71, vcc
	v_sub_f32_e32 v71, v202, v137
	v_cmp_lt_f32_e32 vcc, s22, v228
	v_exp_f32_e32 v71, v71
	v_cvt_pk_bf16_f32 v159, v163, v165
	v_cndmask_b32_e32 v229, 0, v69, vcc
	v_sub_f32_e32 v69, v230, v232
	v_exp_f32_e32 v69, v69
	v_cmp_lt_f32_e32 vcc, s22, v202
	v_cvt_pk_bf16_f32 v202, v166, v168
	v_pk_add_f32 v[178:179], v[222:223], v[178:179]
	v_cndmask_b32_e32 v228, 0, v71, vcc
	v_cmp_lt_f32_e32 vcc, s22, v230
	v_sub_f32_e32 v71, v73, v137
	v_exp_f32_e32 v71, v71
	v_cndmask_b32_e32 v231, 0, v69, vcc
	v_cmp_lt_f32_e32 vcc, s22, v73
	v_add_u32_e32 v73, 0x2000, v65
	ds_read2_b64 v[166:169], v73 offset0:32 offset1:36
	ds_read2_b64 v[170:173], v73 offset0:40 offset1:44
	s_waitcnt lgkmcnt(1)
	v_mfma_f32_16x16x32_bf16 v[40:43], v[166:169], v[200:203], v[40:43]
	v_add_f32_e64 v178, v224, v178
	v_add_f32_e64 v179, v225, v179
	v_cndmask_b32_e32 v230, 0, v71, vcc
	v_pk_add_f32 v[178:179], v[226:227], v[178:179]
	v_mfma_f32_16x16x32_bf16 v[8:11], v[166:169], v[158:161], v[8:11]
	ds_read2_b64 v[166:169], v95 offset0:64 offset1:68
	v_cvt_pk_bf16_f32 v205, v220, v222
	v_cvt_pk_bf16_f32 v206, v224, v226
	v_cvt_pk_bf16_f32 v207, v228, v230
	v_cvt_pk_bf16_f32 v162, v217, v219
	v_cvt_pk_bf16_f32 v163, v221, v223
	v_cvt_pk_bf16_f32 v164, v225, v227
	v_cvt_pk_bf16_f32 v165, v229, v231
	v_pk_add_f32 v[178:179], v[228:229], v[178:179]
	s_waitcnt lgkmcnt(1)
	v_mfma_f32_16x16x32_bf16 v[40:43], v[170:173], v[204:207], v[40:43]
	v_add_f32_e64 v178, v230, v178
	v_add_f32_e64 v179, v231, v179
	v_pk_mul_f32 v[14:15], v[14:15], v[216:217] op_sel_hi:[1,0]
	v_mov_b32_e32 v75, v179
	v_mfma_f32_16x16x32_bf16 v[8:11], v[170:173], v[162:165], v[8:11]
	ds_read2_b64 v[170:173], v95 offset0:72 offset1:76
	v_mov_b32_e32 v73, v179
	v_pk_mul_f32 v[12:13], v[12:13], v[216:217] op_sel_hi:[1,0]
	s_nop 0
	v_permlane16_swap_b32_e32 v75, v73
	v_mfma_f32_16x16x32_bf16 v[44:47], v[208:211], v[200:203], v[44:47]
	v_mul_f32_e64 v6, v6, v216
	v_mul_f32_e64 v7, v7, v216
	v_pk_mul_f32 v[4:5], v[4:5], v[216:217] op_sel_hi:[1,0]
	ds_read2_b64 v[212:215], v65 offset0:8 offset1:12
	v_mfma_f32_16x16x32_bf16 v[12:15], v[208:211], v[158:161], v[12:15]
	v_cndmask_b32_e64 v209, v75, v73, s[8:9]
	v_add_u32_e32 v73, 0x6000, v65
	v_mov_b32_e32 v69, v178
	s_waitcnt lgkmcnt(2)
	v_mfma_f32_16x16x32_bf16 v[36:39], v[166:169], v[200:203], v[36:39]
	v_mov_b32_e32 v71, v178
	v_pk_mul_f32 v[2:3], v[2:3], v[216:217] op_sel_hi:[1,0]
	v_pk_mul_f32 v[0:1], v[0:1], v[216:217] op_sel_hi:[1,0]
	v_mfma_f32_16x16x32_bf16 v[4:7], v[166:169], v[158:161], v[4:7]
	ds_read2_b64 v[166:169], v73 offset0:96 offset1:100
	v_permlane16_swap_b32_e32 v69, v71
	s_waitcnt lgkmcnt(2)
	v_mfma_f32_16x16x32_bf16 v[36:39], v[170:173], v[204:207], v[36:39]
	v_cndmask_b32_e64 v208, v69, v71, s[8:9]
	v_pk_add_f32 v[178:179], v[178:179], v[208:209]
	v_mfma_f32_16x16x32_bf16 v[4:7], v[170:173], v[162:165], v[4:7]
	ds_read2_b64 v[170:173], v73 offset0:104 offset1:108
	v_mov_b32_e32 v69, v178
	v_mov_b32_e32 v71, v178
	s_waitcnt lgkmcnt(1)
	v_mfma_f32_16x16x32_bf16 v[16:19], v[166:169], v[200:203], v[16:19]
	v_mov_b32_e32 v75, v179
	v_mov_b32_e32 v73, v179
	v_permlane32_swap_b32_e32 v69, v71
	v_mfma_f32_16x16x32_bf16 v[0:3], v[166:169], v[158:161], v[0:3]
	v_permlane32_swap_b32_e32 v75, v73
	v_cndmask_b32_e64 v159, v75, v73, s[10:11]
	v_mfma_f32_16x16x32_bf16 v[44:47], v[212:215], v[204:207], v[44:47]
	v_cndmask_b32_e64 v158, v69, v71, s[10:11]
	v_pk_add_f32 v[158:159], v[178:179], v[158:159]
	v_mov_b32_e32 v71, v137
	v_mfma_f32_16x16x32_bf16 v[12:15], v[212:215], v[162:165], v[12:15]
	v_fma_f32 v114, v114, v156, v158
	v_fma_f32 v115, v115, v157, v159
	v_mov_b32_e32 v69, v232
	s_waitcnt lgkmcnt(0)
	v_mfma_f32_16x16x32_bf16 v[16:19], v[170:173], v[204:207], v[16:19]
	v_mfma_f32_16x16x32_bf16 v[0:3], v[170:173], v[162:165], v[0:3]
	s_branch .LBB0_291
